# v3 + SALU hoist above loop-back barrier + LoRA dead-half MFMA skip + grid barrier non-last workgroups spin on TOPGEN (one hop fewer)
# baseline (speedup 1.0000x reference)
.LBB0_95:
	s_or_b64 exec, exec, s[2:3]
	v_cvt_f32_u32_e32 v5, v3
	s_waitcnt vmcnt(0)
	v_readfirstlane_b32 s0, v4
	v_sub_u32_e32 v4, 0, v3
	v_rcp_iflag_f32_e32 v5, v5
	v_add_u32_e32 v6, s0, v2
	v_mul_f32_e32 v5, 0x4f7ffffe, v5
	v_cvt_u32_f32_e32 v5, v5
	v_mul_lo_u32 v2, v4, v5
	v_mul_hi_u32 v2, v5, v2
	v_add_u32_e32 v2, v5, v2
	v_mul_hi_u32 v2, v6, v2
	v_mul_lo_u32 v4, v2, v3
	v_sub_u32_e32 v4, v6, v4
	v_add_u32_e32 v5, 1, v2
	v_cmp_ge_u32_e32 vcc, v4, v3
	s_nop 1
	v_cndmask_b32_e32 v2, v2, v5, vcc
	v_sub_u32_e32 v5, v4, v3
	v_cndmask_b32_e32 v4, v4, v5, vcc
	v_add_u32_e32 v5, 1, v2
	v_cmp_ge_u32_e32 vcc, v4, v3
	v_add_u32_e32 v4, 1, v6
	s_nop 0
	v_cndmask_b32_e32 v2, v2, v5, vcc
	v_mul_lo_u32 v5, v3, v2
	v_add_u32_e32 v3, v5, v3
	v_cmp_ne_u32_e32 vcc, v4, v3
	s_and_saveexec_b64 s[0:1], vcc
	s_xor_b64 s[0:1], exec, s[0:1]
	s_cbranch_execz .LBB0_109
	s_waitcnt lgkmcnt(0)
	v_readlane_b32 s12, v244, 5
	v_readlane_b32 s13, v244, 6
	v_mov_b32_e32 v1, 0
	s_add_u32 s12, s12, 0x7500
	s_addc_u32 s13, s13, 0
	s_nop 0
	global_load_dword v1, v1, s[12:13] sc1
	s_waitcnt vmcnt(0)
	v_cmp_eq_u32_e32 vcc, v1, v2
	s_and_saveexec_b64 s[2:3], vcc
	s_cbranch_execz .LBB0_108
	v_readlane_b32 s10, v244, 5
	v_readlane_b32 s11, v244, 6
	s_add_u32 s10, s10, 0x4200
	s_addc_u32 s11, s11, 0
	s_mov_b32 s24, 1
	s_mov_b64 s[14:15], 0
	v_mov_b32_e32 v1, 0
	s_branch .LBB0_99

.LBB0_687:
	s_or_b64 exec, exec, s[2:3]
	v_cvt_f32_u32_e32 v6, v4
	s_waitcnt vmcnt(0)
	v_readfirstlane_b32 s0, v5
	v_sub_u32_e32 v5, 0, v4
	v_rcp_iflag_f32_e32 v6, v6
	v_add_u32_e32 v7, s0, v3
	v_mul_f32_e32 v6, 0x4f7ffffe, v6
	v_cvt_u32_f32_e32 v6, v6
	v_mul_lo_u32 v3, v5, v6
	v_mul_hi_u32 v3, v6, v3
	v_add_u32_e32 v3, v6, v3
	v_mul_hi_u32 v3, v7, v3
	v_mul_lo_u32 v5, v3, v4
	v_sub_u32_e32 v5, v7, v5
	v_add_u32_e32 v6, 1, v3
	v_cmp_ge_u32_e32 vcc, v5, v4
	s_nop 1
	v_cndmask_b32_e32 v3, v3, v6, vcc
	v_sub_u32_e32 v6, v5, v4
	v_cndmask_b32_e32 v5, v5, v6, vcc
	v_add_u32_e32 v6, 1, v3
	v_cmp_ge_u32_e32 vcc, v5, v4
	v_add_u32_e32 v5, 1, v7
	s_nop 0
	v_cndmask_b32_e32 v3, v3, v6, vcc
	v_mul_lo_u32 v6, v4, v3
	v_add_u32_e32 v4, v6, v4
	v_cmp_ne_u32_e32 vcc, v5, v4
	s_and_saveexec_b64 s[0:1], vcc
	s_xor_b64 s[0:1], exec, s[0:1]
	s_cbranch_execz .LBB0_701
	s_waitcnt lgkmcnt(0)
	v_readlane_b32 s12, v244, 5
	v_readlane_b32 s13, v244, 6
	v_mov_b32_e32 v2, 0
	s_add_u32 s12, s12, 0x7500
	s_addc_u32 s13, s13, 0
	s_nop 0
	global_load_dword v2, v2, s[12:13] sc1
	s_waitcnt vmcnt(0)
	v_cmp_eq_u32_e32 vcc, v2, v3
	s_and_saveexec_b64 s[2:3], vcc
	s_cbranch_execz .LBB0_700
	v_readlane_b32 s10, v244, 5
	v_readlane_b32 s11, v244, 6
	s_add_u32 s10, s10, 0x4200
	s_addc_u32 s11, s11, 0
	s_mov_b32 s24, 1
	s_mov_b64 s[14:15], 0
	v_mov_b32_e32 v2, 0
	s_branch .LBB0_691

.LBB0_925:
	ds_read_b128 v[158:161], v180
	ds_read_b128 v[162:165], v180 offset:1024
	ds_read_b128 v[166:169], v180 offset:2048
	ds_read_b128 v[170:173], v180 offset:3072
	ds_read_b128 v[184:187], v181
	ds_read_b128 v[188:191], v181 offset:1024
	ds_read_b128 v[192:195], v181 offset:2048
	ds_read_b128 v[196:199], v181 offset:3072
	s_add_u32 s0, s4, 0xfff80080
	s_addc_u32 s1, s5, -1
	s_cmp_eq_u32 s26, 28
	s_cselect_b32 s3, s9, s1
	s_cselect_b32 s2, s8, s0
	s_cselect_b32 s1, s25, s23
	s_cselect_b32 s0, s24, s14
	v_lshl_add_u64 v[232:233], s[4:5], 0, v[150:151]
	s_add_i32 m0, s28, 0xc000
	ds_read_b128 v[200:203], v182
	ds_read_b128 v[204:207], v182 offset:1024
	ds_read_b128 v[208:211], v182 offset:2048
	ds_read_b128 v[212:215], v182 offset:3072
	ds_read_b128 v[216:219], v182 offset:4096
	ds_read_b128 v[220:223], v182 offset:5120
	ds_read_b128 v[224:227], v182 offset:6144
	ds_read_b128 v[228:231], v182 offset:7168
	global_load_lds_dwordx4 v[232:233], off
	v_lshl_add_u64 v[232:233], s[4:5], 0, v[152:153]
	s_add_i32 m0, s28, 0xe000
	s_nop 0
	global_load_lds_dwordx4 v[232:233], off
	s_waitcnt vmcnt(8)
	s_waitcnt lgkmcnt(0)
	s_barrier
	s_setprio 1
	s_waitcnt lgkmcnt(0)
	v_mfma_f32_16x16x32_bf16 v[126:129], v[158:161], v[200:203], v[126:129]
	v_mfma_f32_16x16x32_bf16 v[122:125], v[166:169], v[200:203], v[122:125]
	v_mfma_f32_16x16x32_bf16 v[118:121], v[158:161], v[208:211], v[118:121]
	v_mfma_f32_16x16x32_bf16 v[114:117], v[166:169], v[208:211], v[114:117]
	v_mfma_f32_16x16x32_bf16 v[102:105], v[158:161], v[216:219], v[102:105]
	v_mfma_f32_16x16x32_bf16 v[98:101], v[166:169], v[216:219], v[98:101]
	v_mfma_f32_16x16x32_bf16 v[86:89], v[158:161], v[224:227], v[86:89]
	v_mfma_f32_16x16x32_bf16 v[82:85], v[166:169], v[224:227], v[82:85]
	v_mfma_f32_16x16x32_bf16 v[126:129], v[162:165], v[204:207], v[126:129]
	v_mfma_f32_16x16x32_bf16 v[122:125], v[170:173], v[204:207], v[122:125]
	v_mfma_f32_16x16x32_bf16 v[118:121], v[162:165], v[212:215], v[118:121]
	v_mfma_f32_16x16x32_bf16 v[114:117], v[170:173], v[212:215], v[114:117]
	v_mfma_f32_16x16x32_bf16 v[102:105], v[162:165], v[220:223], v[102:105]
	v_mfma_f32_16x16x32_bf16 v[98:101], v[170:173], v[220:223], v[98:101]
	v_mfma_f32_16x16x32_bf16 v[86:89], v[162:165], v[228:231], v[86:89]
	v_mfma_f32_16x16x32_bf16 v[82:85], v[170:173], v[228:231], v[82:85]
	s_setprio 0
	s_setprio 1
	s_cmp_gt_u32 s52, 31
	s_cbranch_scc1 .Lmy_lora_skip_0
	v_mfma_f32_16x16x32_bf16 v[110:113], v[184:187], v[200:203], v[110:113]
	v_mfma_f32_16x16x32_bf16 v[106:109], v[192:195], v[200:203], v[106:109]
	v_mfma_f32_16x16x32_bf16 v[94:97], v[184:187], v[208:211], v[94:97]
	v_mfma_f32_16x16x32_bf16 v[90:93], v[192:195], v[208:211], v[90:93]
	v_mfma_f32_16x16x32_bf16 v[78:81], v[184:187], v[216:219], v[78:81]
	v_mfma_f32_16x16x32_bf16 v[74:77], v[192:195], v[216:219], v[74:77]
	v_mfma_f32_16x16x32_bf16 v[70:73], v[184:187], v[224:227], v[70:73]
	v_mfma_f32_16x16x32_bf16 v[66:69], v[192:195], v[224:227], v[66:69]
	v_mfma_f32_16x16x32_bf16 v[110:113], v[188:191], v[204:207], v[110:113]
	v_mfma_f32_16x16x32_bf16 v[106:109], v[196:199], v[204:207], v[106:109]
	v_mfma_f32_16x16x32_bf16 v[94:97], v[188:191], v[212:215], v[94:97]
	v_mfma_f32_16x16x32_bf16 v[90:93], v[196:199], v[212:215], v[90:93]
	v_mfma_f32_16x16x32_bf16 v[78:81], v[188:191], v[220:223], v[78:81]
	v_mfma_f32_16x16x32_bf16 v[74:77], v[196:199], v[220:223], v[74:77]
	v_mfma_f32_16x16x32_bf16 v[70:73], v[188:191], v[228:231], v[70:73]
	v_mfma_f32_16x16x32_bf16 v[66:69], v[196:199], v[228:231], v[66:69]
.Lmy_lora_skip_0:
	s_setprio 0
	s_barrier
	s_add_i32 s27, s47, s13
	v_lshl_add_u64 v[232:233], s[0:1], 0, v[136:137]
	s_mov_b32 m0, s27
	ds_read_b128 v[200:203], v182 offset:16384
	ds_read_b128 v[204:207], v182 offset:17408
	ds_read_b128 v[208:211], v182 offset:18432
	ds_read_b128 v[212:215], v182 offset:19456
	ds_read_b128 v[216:219], v182 offset:20480
	ds_read_b128 v[220:223], v182 offset:21504
	ds_read_b128 v[224:227], v182 offset:22528
	ds_read_b128 v[228:231], v182 offset:23552
	global_load_lds_dwordx4 v[232:233], off
	s_add_i32 m0, s27, 0x2000
	s_add_u32 s54, s0, 0x80000
	v_lshl_add_u64 v[234:235], s[0:1], 0, v[142:143]
	s_addc_u32 s55, s1, 0
	s_add_i32 s27, s48, s13
	global_load_lds_dwordx4 v[234:235], off
	v_lshl_add_u64 v[236:237], s[54:55], 0, v[136:137]
	s_mov_b32 m0, s27
	v_lshl_add_u64 v[238:239], s[2:3], 0, v[140:141]
	global_load_lds_dwordx4 v[236:237], off
	v_lshl_add_u64 v[236:237], s[54:55], 0, v[142:143]
	s_add_i32 m0, s27, 0x2000
	s_nop 0
	global_load_lds_dwordx4 v[236:237], off
	v_lshl_add_u64 v[236:237], s[2:3], 0, v[134:135]
	s_mov_b32 m0, s28
	s_nop 0
	global_load_lds_dwordx4 v[236:237], off
	s_mov_b32 m0, s29
	s_nop 0
	global_load_lds_dwordx4 v[238:239], off
	s_waitcnt vmcnt(8)
	s_waitcnt lgkmcnt(0)
	s_barrier
	s_setprio 1
	s_waitcnt lgkmcnt(0)
	v_mfma_f32_16x16x32_bf16 v[62:65], v[158:161], v[200:203], v[62:65]
	v_mfma_f32_16x16x32_bf16 v[58:61], v[166:169], v[200:203], v[58:61]
	v_mfma_f32_16x16x32_bf16 v[54:57], v[158:161], v[208:211], v[54:57]
	v_mfma_f32_16x16x32_bf16 v[50:53], v[166:169], v[208:211], v[50:53]
	v_mfma_f32_16x16x32_bf16 v[38:41], v[158:161], v[216:219], v[38:41]
	v_mfma_f32_16x16x32_bf16 v[34:37], v[166:169], v[216:219], v[34:37]
	v_mfma_f32_16x16x32_bf16 v[22:25], v[158:161], v[224:227], v[22:25]
	v_mfma_f32_16x16x32_bf16 v[18:21], v[166:169], v[224:227], v[18:21]
	v_mfma_f32_16x16x32_bf16 v[62:65], v[162:165], v[204:207], v[62:65]
	v_mfma_f32_16x16x32_bf16 v[58:61], v[170:173], v[204:207], v[58:61]
	v_mfma_f32_16x16x32_bf16 v[54:57], v[162:165], v[212:215], v[54:57]
	v_mfma_f32_16x16x32_bf16 v[50:53], v[170:173], v[212:215], v[50:53]
	v_mfma_f32_16x16x32_bf16 v[38:41], v[162:165], v[220:223], v[38:41]
	v_mfma_f32_16x16x32_bf16 v[34:37], v[170:173], v[220:223], v[34:37]
	v_mfma_f32_16x16x32_bf16 v[22:25], v[162:165], v[228:231], v[22:25]
	v_mfma_f32_16x16x32_bf16 v[18:21], v[170:173], v[228:231], v[18:21]
	s_setprio 0
	s_setprio 1
	s_cmp_gt_u32 s52, 31
	s_cbranch_scc1 .Lmy_lora_skip_1
	v_mfma_f32_16x16x32_bf16 v[46:49], v[184:187], v[200:203], v[46:49]
	v_mfma_f32_16x16x32_bf16 v[42:45], v[192:195], v[200:203], v[42:45]
	v_mfma_f32_16x16x32_bf16 v[30:33], v[184:187], v[208:211], v[30:33]
	v_mfma_f32_16x16x32_bf16 v[26:29], v[192:195], v[208:211], v[26:29]
	v_mfma_f32_16x16x32_bf16 v[14:17], v[184:187], v[216:219], v[14:17]
	v_mfma_f32_16x16x32_bf16 v[10:13], v[192:195], v[216:219], v[10:13]
	v_mfma_f32_16x16x32_bf16 v[6:9], v[184:187], v[224:227], v[6:9]
	v_mfma_f32_16x16x32_bf16 v[2:5], v[192:195], v[224:227], v[2:5]
	v_mfma_f32_16x16x32_bf16 v[46:49], v[188:191], v[204:207], v[46:49]
	v_mfma_f32_16x16x32_bf16 v[42:45], v[196:199], v[204:207], v[42:45]
	v_mfma_f32_16x16x32_bf16 v[30:33], v[188:191], v[212:215], v[30:33]
	v_mfma_f32_16x16x32_bf16 v[26:29], v[196:199], v[212:215], v[26:29]
	v_mfma_f32_16x16x32_bf16 v[14:17], v[188:191], v[220:223], v[14:17]
	v_mfma_f32_16x16x32_bf16 v[10:13], v[196:199], v[220:223], v[10:13]
	v_mfma_f32_16x16x32_bf16 v[6:9], v[188:191], v[228:231], v[6:9]
	v_mfma_f32_16x16x32_bf16 v[2:5], v[196:199], v[228:231], v[2:5]
.Lmy_lora_skip_1:
	s_setprio 0
	s_barrier
	s_add_i32 s27, 0, 0x18000
	v_add_u32_e32 v144, s27, v179
	s_add_i32 s53, 0, 0x1c000
	ds_read_b128 v[158:161], v144
	ds_read_b128 v[162:165], v144 offset:1024
	ds_read_b128 v[166:169], v144 offset:2048
	ds_read_b128 v[170:173], v144 offset:3072
	v_add_u32_e32 v144, s53, v179
	ds_read_b128 v[184:187], v144
	ds_read_b128 v[188:191], v144 offset:1024
	ds_read_b128 v[192:195], v144 offset:2048
	ds_read_b128 v[196:199], v144 offset:3072
	s_add_u32 s2, s2, 0x80000
	s_addc_u32 s3, s3, 0
	s_mov_b32 m0, s30
	v_lshl_add_u64 v[240:241], s[2:3], 0, v[134:135]
	ds_read_b128 v[200:203], v182 offset:32768
	ds_read_b128 v[204:207], v182 offset:33792
	ds_read_b128 v[208:211], v182 offset:34816
	ds_read_b128 v[212:215], v182 offset:35840
	ds_read_b128 v[216:219], v182 offset:36864
	ds_read_b128 v[220:223], v182 offset:37888
	ds_read_b128 v[224:227], v182 offset:38912
	ds_read_b128 v[228:231], v182 offset:39936
	global_load_lds_dwordx4 v[240:241], off
	v_lshl_add_u64 v[240:241], s[2:3], 0, v[140:141]
	s_mov_b32 m0, s31
	s_nop 0
	global_load_lds_dwordx4 v[240:241], off
	s_waitcnt vmcnt(8)
	s_waitcnt lgkmcnt(0)
	s_barrier
	s_setprio 1
	s_waitcnt lgkmcnt(0)
	v_mfma_f32_16x16x32_bf16 v[126:129], v[158:161], v[200:203], v[126:129]
	v_mfma_f32_16x16x32_bf16 v[122:125], v[166:169], v[200:203], v[122:125]
	v_mfma_f32_16x16x32_bf16 v[118:121], v[158:161], v[208:211], v[118:121]
	v_mfma_f32_16x16x32_bf16 v[114:117], v[166:169], v[208:211], v[114:117]
	v_mfma_f32_16x16x32_bf16 v[102:105], v[158:161], v[216:219], v[102:105]
	v_mfma_f32_16x16x32_bf16 v[98:101], v[166:169], v[216:219], v[98:101]
	v_mfma_f32_16x16x32_bf16 v[86:89], v[158:161], v[224:227], v[86:89]
	v_mfma_f32_16x16x32_bf16 v[82:85], v[166:169], v[224:227], v[82:85]
	v_mfma_f32_16x16x32_bf16 v[126:129], v[162:165], v[204:207], v[126:129]
	v_mfma_f32_16x16x32_bf16 v[122:125], v[170:173], v[204:207], v[122:125]
	v_mfma_f32_16x16x32_bf16 v[118:121], v[162:165], v[212:215], v[118:121]
	v_mfma_f32_16x16x32_bf16 v[114:117], v[170:173], v[212:215], v[114:117]
	v_mfma_f32_16x16x32_bf16 v[102:105], v[162:165], v[220:223], v[102:105]
	v_mfma_f32_16x16x32_bf16 v[98:101], v[170:173], v[220:223], v[98:101]
	v_mfma_f32_16x16x32_bf16 v[86:89], v[162:165], v[228:231], v[86:89]
	v_mfma_f32_16x16x32_bf16 v[82:85], v[170:173], v[228:231], v[82:85]
	s_setprio 0
	s_setprio 1
	s_cmp_gt_u32 s52, 31
	s_cbranch_scc1 .Lmy_lora_skip_2
	v_mfma_f32_16x16x32_bf16 v[110:113], v[184:187], v[200:203], v[110:113]
	v_mfma_f32_16x16x32_bf16 v[106:109], v[192:195], v[200:203], v[106:109]
	v_mfma_f32_16x16x32_bf16 v[94:97], v[184:187], v[208:211], v[94:97]
	v_mfma_f32_16x16x32_bf16 v[90:93], v[192:195], v[208:211], v[90:93]
	v_mfma_f32_16x16x32_bf16 v[78:81], v[184:187], v[216:219], v[78:81]
	v_mfma_f32_16x16x32_bf16 v[74:77], v[192:195], v[216:219], v[74:77]
	v_mfma_f32_16x16x32_bf16 v[70:73], v[184:187], v[224:227], v[70:73]
	v_mfma_f32_16x16x32_bf16 v[66:69], v[192:195], v[224:227], v[66:69]
	v_mfma_f32_16x16x32_bf16 v[110:113], v[188:191], v[204:207], v[110:113]
	v_mfma_f32_16x16x32_bf16 v[106:109], v[196:199], v[204:207], v[106:109]
	v_mfma_f32_16x16x32_bf16 v[94:97], v[188:191], v[212:215], v[94:97]
	v_mfma_f32_16x16x32_bf16 v[90:93], v[196:199], v[212:215], v[90:93]
	v_mfma_f32_16x16x32_bf16 v[78:81], v[188:191], v[220:223], v[78:81]
	v_mfma_f32_16x16x32_bf16 v[74:77], v[196:199], v[220:223], v[74:77]
	v_mfma_f32_16x16x32_bf16 v[70:73], v[188:191], v[228:231], v[70:73]
	v_mfma_f32_16x16x32_bf16 v[66:69], v[196:199], v[228:231], v[66:69]
.Lmy_lora_skip_2:
	s_setprio 0
	s_barrier
	s_add_i32 s2, s27, s13
	v_lshl_add_u64 v[232:233], v[232:233], 0, s[18:19]
	s_mov_b32 m0, s2
	ds_read_b128 v[200:203], v182 offset:49152
	ds_read_b128 v[204:207], v182 offset:50176
	ds_read_b128 v[208:211], v182 offset:51200
	ds_read_b128 v[212:215], v182 offset:52224
	ds_read_b128 v[216:219], v182 offset:53248
	ds_read_b128 v[220:223], v182 offset:54272
	ds_read_b128 v[224:227], v182 offset:55296
	ds_read_b128 v[228:231], v182 offset:56320
	global_load_lds_dwordx4 v[232:233], off
	s_add_i32 m0, s2, 0x2000
	s_add_u32 s0, s0, 0x80080
	v_lshl_add_u64 v[232:233], v[234:235], 0, s[18:19]
	s_addc_u32 s1, s1, 0
	s_add_i32 s2, s53, s13
	global_load_lds_dwordx4 v[232:233], off
	v_lshl_add_u64 v[232:233], s[0:1], 0, v[136:137]
	s_mov_b32 m0, s2
	s_nop 0
	global_load_lds_dwordx4 v[232:233], off
	v_lshl_add_u64 v[232:233], s[0:1], 0, v[142:143]
	s_add_i32 m0, s2, 0x2000
	s_nop 0
	global_load_lds_dwordx4 v[232:233], off
	v_lshl_add_u64 v[232:233], v[236:237], 0, s[18:19]
	s_mov_b32 m0, s33
	s_nop 0
	global_load_lds_dwordx4 v[232:233], off
	v_lshl_add_u64 v[232:233], v[238:239], 0, s[18:19]
	s_mov_b32 m0, s34
	s_nop 0
	global_load_lds_dwordx4 v[232:233], off
	s_waitcnt vmcnt(8)
	s_waitcnt lgkmcnt(0)
	s_barrier
	s_setprio 1
	s_waitcnt lgkmcnt(0)
	v_mfma_f32_16x16x32_bf16 v[62:65], v[158:161], v[200:203], v[62:65]
	v_mfma_f32_16x16x32_bf16 v[58:61], v[166:169], v[200:203], v[58:61]
	v_mfma_f32_16x16x32_bf16 v[54:57], v[158:161], v[208:211], v[54:57]
	v_mfma_f32_16x16x32_bf16 v[50:53], v[166:169], v[208:211], v[50:53]
	v_mfma_f32_16x16x32_bf16 v[38:41], v[158:161], v[216:219], v[38:41]
	v_mfma_f32_16x16x32_bf16 v[34:37], v[166:169], v[216:219], v[34:37]
	v_mfma_f32_16x16x32_bf16 v[22:25], v[158:161], v[224:227], v[22:25]
	v_mfma_f32_16x16x32_bf16 v[18:21], v[166:169], v[224:227], v[18:21]
	v_mfma_f32_16x16x32_bf16 v[62:65], v[162:165], v[204:207], v[62:65]
	v_mfma_f32_16x16x32_bf16 v[58:61], v[170:173], v[204:207], v[58:61]
	v_mfma_f32_16x16x32_bf16 v[54:57], v[162:165], v[212:215], v[54:57]
	v_mfma_f32_16x16x32_bf16 v[50:53], v[170:173], v[212:215], v[50:53]
	v_mfma_f32_16x16x32_bf16 v[38:41], v[162:165], v[220:223], v[38:41]
	v_mfma_f32_16x16x32_bf16 v[34:37], v[170:173], v[220:223], v[34:37]
	v_mfma_f32_16x16x32_bf16 v[22:25], v[162:165], v[228:231], v[22:25]
	v_mfma_f32_16x16x32_bf16 v[18:21], v[170:173], v[228:231], v[18:21]
	s_setprio 0
	s_setprio 1
	s_cmp_gt_u32 s52, 31
	s_cbranch_scc1 .Lmy_lora_skip_3
	v_mfma_f32_16x16x32_bf16 v[46:49], v[184:187], v[200:203], v[46:49]
	v_mfma_f32_16x16x32_bf16 v[42:45], v[192:195], v[200:203], v[42:45]
	v_mfma_f32_16x16x32_bf16 v[30:33], v[184:187], v[208:211], v[30:33]
	v_mfma_f32_16x16x32_bf16 v[26:29], v[192:195], v[208:211], v[26:29]
	v_mfma_f32_16x16x32_bf16 v[14:17], v[184:187], v[216:219], v[14:17]
	v_mfma_f32_16x16x32_bf16 v[10:13], v[192:195], v[216:219], v[10:13]
	v_mfma_f32_16x16x32_bf16 v[6:9], v[184:187], v[224:227], v[6:9]
	v_mfma_f32_16x16x32_bf16 v[2:5], v[192:195], v[224:227], v[2:5]
	v_mfma_f32_16x16x32_bf16 v[46:49], v[188:191], v[204:207], v[46:49]
	v_mfma_f32_16x16x32_bf16 v[42:45], v[196:199], v[204:207], v[42:45]
	v_mfma_f32_16x16x32_bf16 v[30:33], v[188:191], v[212:215], v[30:33]
	v_mfma_f32_16x16x32_bf16 v[26:29], v[196:199], v[212:215], v[26:29]
	v_mfma_f32_16x16x32_bf16 v[14:17], v[188:191], v[220:223], v[14:17]
	v_mfma_f32_16x16x32_bf16 v[10:13], v[196:199], v[220:223], v[10:13]
	v_mfma_f32_16x16x32_bf16 v[6:9], v[188:191], v[228:231], v[6:9]
	v_mfma_f32_16x16x32_bf16 v[2:5], v[196:199], v[228:231], v[2:5]
.Lmy_lora_skip_3:
	s_setprio 0
	s_add_i32 s26, s26, 2
	s_add_u32 s4, s4, 0x100
	s_addc_u32 s5, s5, 0
	s_add_u32 s14, s14, 0x100
	s_addc_u32 s23, s23, 0
	s_cmp_gt_u32 s26, 29
	s_barrier
	s_cbranch_scc0 .LBB0_925
	s_and_b64 vcc, exec, s[20:21]
	s_cbranch_vccz .LBB0_928
	s_barrier

.LBB0_1378:
	s_or_b64 exec, exec, s[2:3]
	v_cvt_f32_u32_e32 v4, v2
	s_waitcnt vmcnt(0)
	v_readfirstlane_b32 s0, v3
	v_sub_u32_e32 v3, 0, v2
	v_rcp_iflag_f32_e32 v4, v4
	v_add_u32_e32 v5, s0, v1
	v_mul_f32_e32 v4, 0x4f7ffffe, v4
	v_cvt_u32_f32_e32 v4, v4
	v_mul_lo_u32 v1, v3, v4
	v_mul_hi_u32 v1, v4, v1
	v_add_u32_e32 v1, v4, v1
	v_mul_hi_u32 v1, v5, v1
	v_mul_lo_u32 v3, v1, v2
	v_sub_u32_e32 v3, v5, v3
	v_add_u32_e32 v4, 1, v1
	v_cmp_ge_u32_e32 vcc, v3, v2
	s_nop 1
	v_cndmask_b32_e32 v1, v1, v4, vcc
	v_sub_u32_e32 v4, v3, v2
	v_cndmask_b32_e32 v3, v3, v4, vcc
	v_add_u32_e32 v4, 1, v1
	v_cmp_ge_u32_e32 vcc, v3, v2
	v_add_u32_e32 v3, 1, v5
	s_nop 0
	v_cndmask_b32_e32 v1, v1, v4, vcc
	v_mul_lo_u32 v4, v2, v1
	v_add_u32_e32 v2, v4, v2
	v_cmp_ne_u32_e32 vcc, v3, v2
	s_and_saveexec_b64 s[0:1], vcc
	s_xor_b64 s[0:1], exec, s[0:1]
	s_cbranch_execz .LBB0_1392
	s_waitcnt lgkmcnt(0)
	v_readlane_b32 s12, v244, 5
	v_readlane_b32 s13, v244, 6
	v_mov_b32_e32 v0, 0
	s_add_u32 s12, s12, 0x7500
	s_addc_u32 s13, s13, 0
	s_nop 0
	global_load_dword v0, v0, s[12:13] sc1
	s_waitcnt vmcnt(0)
	v_cmp_eq_u32_e32 vcc, v0, v1
	s_and_saveexec_b64 s[2:3], vcc
	s_cbranch_execz .LBB0_1391
	v_readlane_b32 s10, v244, 5
	v_readlane_b32 s11, v244, 6
	s_add_u32 s10, s10, 0x4200
	s_addc_u32 s11, s11, 0
	s_mov_b32 s24, 1
	s_mov_b64 s[14:15], 0
	v_mov_b32_e32 v0, 0
	s_branch .LBB0_1382
